# v27 + hand-written residual-GEMM epilogue (4-deep pipelined X loads, batched partial-sum shuffles, 40% fewer instructions)
# speedup vs baseline: 1.0042x; 1.0042x over previous
;     __device__ __forceinline__ void operator()(const f32x4 (&acc)[2][2][4][2], const pg8::Unit& u, int wr, int wc, int fr, int fq) const {
;         const int row0 = u.pm * 256 + wr * 64 + fr, col0 = u.pn * 256 + wc * 32 + 8 * fq;
;         const float* gsel = gin ? gin : gout;
;         f32x4 gv[2][2];
; #pragma unroll
;         for (int bj = 0; bj < 2; ++bj)
; #pragma unroll
;             for (int n = 0; n < 2; ++n) gv[bj][n] = gsel ? *(const f32x4*)(gsel + col0 + bj * 128 + 4 * n) : (f32x4){1.f, 1.f, 1.f, 1.f};
; #pragma unroll
;         for (int am = 0; am < 4; ++am) {
;             const int ai = am >> 1, mb = (am & 1) * 2;
;             u32x4 xr[2][2]; float rin[2];
; #pragma unroll
;             for (int mm = 0; mm < 2; ++mm) {
;                 rin[mm] = gin ? tabin[u.idx * 256 + wr * 64 + fr + ai * 128 + (mb + mm) * 16] : 1.0f;
; #pragma unroll
;                 for (int bj = 0; bj < 2; ++bj) xr[mm][bj] = *(const u32x4*)(X + (size_t)(row0 + ai * 128 + (mb + mm) * 16) * D + col0 + bj * 128);
;             }
; #pragma unroll
;             for (int mm = 0; mm < 2; ++mm) {
;                 float ss = 0.f, ss2 = 0.f;
; #pragma unroll
;                 for (int bj = 0; bj < 2; ++bj) {
;                     const f32x4 a0 = acc[ai][bj][mb + mm][0], a1 = acc[ai][bj][mb + mm][1]; const u32x4 x = xr[mm][bj]; u32x4 w;
;                     f32x4 x0 = {bflo(x.x), bfhi(x.x), bflo(x.y), bfhi(x.y)}, x1 = {bflo(x.z), bfhi(x.z), bflo(x.w), bfhi(x.w)};
;                     if (gin) { x0 = x0 * rin[mm] * gv[bj][0]; x1 = x1 * rin[mm] * gv[bj][1]; }
;                     const f32x4 y0 = x0 + a0 * scale, y1 = x1 + a1 * scale;
;                     ss += ((y0[0] * y0[0] + y0[1] * y0[1]) + (y0[2] * y0[2] + y0[3] * y0[3])) + ((y1[0] * y1[0] + y1[1] * y1[1]) + (y1[2] * y1[2] + y1[3] * y1[3]));
;                     if (part2) { const f32x4 z0 = y0 * gv[bj][0], z1 = y1 * gv[bj][1];
;                         ss2 += ((z0[0] * z0[0] + z0[1] * z0[1]) + (z0[2] * z0[2] + z0[3] * z0[3])) + ((z1[0] * z1[0] + z1[1] * z1[1]) + (z1[2] * z1[2] + z1[3] * z1[3])); }
;                     w.x = pg8::cvt_pk_bf16(y0[0], y0[1]); w.y = pg8::cvt_pk_bf16(y0[2], y0[3]); w.z = pg8::cvt_pk_bf16(y1[0], y1[1]); w.w = pg8::cvt_pk_bf16(y1[2], y1[3]);
;                     *(u32x4*)(X + (size_t)(row0 + ai * 128 + (mb + mm) * 16) * D + col0 + bj * 128) = w;
.LBB0_511:
	v_lshl_or_b32 v194, s52, 8, v216
	v_lshl_add_u32 v198, s25, 8, v81
	s_lshl_b32 s0, s0, 10
	s_lshl_b32 s26, s52, 4
	s_lshl_b32 s27, s63, 2
	s_add_i32 s26, s26, s27
	v_lshlrev_b32_e32 v232, 11, v198
	v_add_u32_e32 v217, s0, v247
	v_lshl_add_u32 v232, v194, 1, v232
	v_lshl_add_u32 v233, v198, 6, s26
	s_and_b64 vcc, exec, s[84:85]
	s_cbranch_vccz .Lrz_nogv
	v_lshlrev_b32_e32 v234, 2, v194
	global_load_dwordx4 v[40:43], v234, s[82:83]
	global_load_dwordx4 v[44:47], v234, s[82:83] offset:16
	global_load_dwordx4 v[52:55], v234, s[82:83] offset:512
	global_load_dwordx4 v[60:63], v234, s[82:83] offset:528
.Lrz_nogv:
	v_add_u32_e32 v234, 0x0, v232
	global_load_dwordx4 v[146:149], v234, s[54:55]
	global_load_dwordx4 v[150:153], v234, s[54:55] offset:256
	v_add_u32_e32 v234, 0x8000, v232
	global_load_dwordx4 v[154:157], v234, s[54:55]
	global_load_dwordx4 v[158:161], v234, s[54:55] offset:256
	v_add_u32_e32 v234, 0x10000, v232
	global_load_dwordx4 v[194:197], v234, s[54:55]
	global_load_dwordx4 v[198:201], v234, s[54:55] offset:256
	v_add_u32_e32 v234, 0x18000, v232
	global_load_dwordx4 v[202:205], v234, s[54:55]
	global_load_dwordx4 v[206:209], v234, s[54:55] offset:256
	s_and_b64 vcc, exec, s[80:81]
	s_cbranch_vccz .Lrz_norin_0
	ds_read_b32 v235, v217
.Lrz_norin_0:
	s_waitcnt vmcnt(6)
	v_lshlrev_b32_e32 v178, 16, v146
	v_and_b32_e32 v179, 0xffff0000, v146
	v_lshlrev_b32_e32 v180, 16, v147
	v_and_b32_e32 v181, 0xffff0000, v147
	v_lshlrev_b32_e32 v182, 16, v148
	v_and_b32_e32 v183, 0xffff0000, v148
	v_lshlrev_b32_e32 v184, 16, v149
	v_and_b32_e32 v185, 0xffff0000, v149
	v_lshlrev_b32_e32 v210, 16, v150
	v_and_b32_e32 v211, 0xffff0000, v150
	v_lshlrev_b32_e32 v212, 16, v151
	v_and_b32_e32 v213, 0xffff0000, v151
	v_lshlrev_b32_e32 v226, 16, v152
	v_and_b32_e32 v227, 0xffff0000, v152
	v_lshlrev_b32_e32 v228, 16, v153
	v_and_b32_e32 v229, 0xffff0000, v153
	v_add_u32_e32 v234, 0x40000, v232
	global_load_dwordx4 v[146:149], v234, s[54:55]
	global_load_dwordx4 v[150:153], v234, s[54:55] offset:256
	s_and_b64 vcc, exec, s[80:81]
	s_cbranch_vccz .Lrz_nolazy_0
	s_waitcnt lgkmcnt(0)
	v_mul_f32_e32 v178, v235, v178
	v_mul_f32_e32 v179, v235, v179
	v_mul_f32_e32 v180, v235, v180
	v_mul_f32_e32 v181, v235, v181
	v_mul_f32_e32 v182, v235, v182
	v_mul_f32_e32 v183, v235, v183
	v_mul_f32_e32 v184, v235, v184
	v_mul_f32_e32 v185, v235, v185
	v_pk_mul_f32 v[178:179], v[178:179], v[40:41]
	v_pk_mul_f32 v[180:181], v[180:181], v[42:43]
	v_pk_mul_f32 v[182:183], v[182:183], v[44:45]
	v_pk_mul_f32 v[184:185], v[184:185], v[46:47]
	v_mul_f32_e32 v210, v235, v210
	v_mul_f32_e32 v211, v235, v211
	v_mul_f32_e32 v212, v235, v212
	v_mul_f32_e32 v213, v235, v213
	v_mul_f32_e32 v226, v235, v226
	v_mul_f32_e32 v227, v235, v227
	v_mul_f32_e32 v228, v235, v228
	v_mul_f32_e32 v229, v235, v229
	v_pk_mul_f32 v[210:211], v[210:211], v[52:53]
	v_pk_mul_f32 v[212:213], v[212:213], v[54:55]
	v_pk_mul_f32 v[226:227], v[226:227], v[60:61]
	v_pk_mul_f32 v[228:229], v[228:229], v[62:63]
.Lrz_nolazy_0:
	v_pk_fma_f32 v[142:143], v[172:173], v[142:143], v[178:179]
	v_pk_fma_f32 v[144:145], v[172:173], v[144:145], v[180:181]
	v_pk_fma_f32 v[138:139], v[172:173], v[138:139], v[182:183]
	v_pk_fma_f32 v[140:141], v[172:173], v[140:141], v[184:185]
	v_pk_fma_f32 v[134:135], v[172:173], v[134:135], v[210:211]
	v_pk_fma_f32 v[136:137], v[172:173], v[136:137], v[212:213]
	v_pk_fma_f32 v[130:131], v[172:173], v[130:131], v[226:227]
	v_pk_fma_f32 v[132:133], v[172:173], v[132:133], v[228:229]
	v_add_u32_e32 v234, 0x0, v232
	v_cvt_pk_bf16_f32 v178, v142, v143
	v_cvt_pk_bf16_f32 v179, v144, v145
	v_cvt_pk_bf16_f32 v180, v138, v139
	v_cvt_pk_bf16_f32 v181, v140, v141
	global_store_dwordx4 v234, v[178:181], s[54:55]
	v_cvt_pk_bf16_f32 v182, v134, v135
	v_cvt_pk_bf16_f32 v183, v136, v137
	v_cvt_pk_bf16_f32 v184, v130, v131
	v_cvt_pk_bf16_f32 v185, v132, v133
	global_store_dwordx4 v234, v[182:185], s[54:55] offset:256
	v_mul_f32_e32 v210, v142, v142
	v_mul_f32_e32 v211, v143, v143
	v_fmac_f32_e32 v210, v144, v144
	v_fmac_f32_e32 v211, v145, v145
	v_fmac_f32_e32 v210, v138, v138
	v_fmac_f32_e32 v211, v139, v139
	v_fmac_f32_e32 v210, v140, v140
	v_fmac_f32_e32 v211, v141, v141
	v_fmac_f32_e32 v210, v134, v134
	v_fmac_f32_e32 v211, v135, v135
	v_fmac_f32_e32 v210, v136, v136
	v_fmac_f32_e32 v211, v137, v137
	v_fmac_f32_e32 v210, v130, v130
	v_fmac_f32_e32 v211, v131, v131
	v_fmac_f32_e32 v210, v132, v132
	v_fmac_f32_e32 v211, v133, v133
	s_and_b64 vcc, exec, s[74:75]
	s_cbranch_vccz .Lrz_nop2_0
	v_pk_mul_f32 v[212:213], v[142:143], v[40:41]
	v_mul_f32_e32 v226, v212, v212
	v_mul_f32_e32 v227, v213, v213
	v_pk_mul_f32 v[212:213], v[144:145], v[42:43]
	v_fmac_f32_e32 v226, v212, v212
	v_fmac_f32_e32 v227, v213, v213
	v_pk_mul_f32 v[212:213], v[138:139], v[44:45]
	v_fmac_f32_e32 v226, v212, v212
	v_fmac_f32_e32 v227, v213, v213
	v_pk_mul_f32 v[212:213], v[140:141], v[46:47]
	v_fmac_f32_e32 v226, v212, v212
	v_fmac_f32_e32 v227, v213, v213
	v_pk_mul_f32 v[212:213], v[134:135], v[52:53]
	v_fmac_f32_e32 v226, v212, v212
	v_fmac_f32_e32 v227, v213, v213
	v_pk_mul_f32 v[212:213], v[136:137], v[54:55]
	v_fmac_f32_e32 v226, v212, v212
	v_fmac_f32_e32 v227, v213, v213
	v_pk_mul_f32 v[212:213], v[130:131], v[60:61]
	v_fmac_f32_e32 v226, v212, v212
	v_fmac_f32_e32 v227, v213, v213
	v_pk_mul_f32 v[212:213], v[132:133], v[62:63]
	v_fmac_f32_e32 v226, v212, v212
	v_fmac_f32_e32 v227, v213, v213
	v_add_f32_e32 v134, v226, v227
.Lrz_nop2_0:
	v_add_f32_e32 v142, v210, v211
	s_and_b64 vcc, exec, s[80:81]
	s_cbranch_vccz .Lrz_norin_1
	ds_read_b32 v235, v217 offset:64
; __device__ __forceinline__ unsigned cvt_pk_bf16(float lo, float hi) { unsigned r; asm volatile("v_cvt_pk_bf16_f32 %0, %1, %2" : "=v"(r) : "v"(lo), "v"(hi)); return r; }
;     __device__ __forceinline__ void operator()(const f32x4 (&acc)[2][2][4][2], const pg8::Unit& u, int wr, int wc, int fr, int fq) const {
;     ...
;         for (int am = 0; am < 4; ++am) {
;             const int ai = am >> 1, mb = (am & 1) * 2;
;             u32x4 xr[2][2]; float rin[2];
; #pragma unroll
;             for (int mm = 0; mm < 2; ++mm) {
;                 rin[mm] = gin ? tabin[u.idx * 256 + wr * 64 + fr + ai * 128 + (mb + mm) * 16] : 1.0f;
; #pragma unroll
;                 for (int bj = 0; bj < 2; ++bj) xr[mm][bj] = *(const u32x4*)(X + (size_t)(row0 + ai * 128 + (mb + mm) * 16) * D + col0 + bj * 128);
;             }
; #pragma unroll
;             for (int mm = 0; mm < 2; ++mm) {
;                 float ss = 0.f, ss2 = 0.f;
; #pragma unroll
;                 for (int bj = 0; bj < 2; ++bj) {
;                     const f32x4 a0 = acc[ai][bj][mb + mm][0], a1 = acc[ai][bj][mb + mm][1]; const u32x4 x = xr[mm][bj]; u32x4 w;
;                     f32x4 x0 = {bflo(x.x), bfhi(x.x), bflo(x.y), bfhi(x.y)}, x1 = {bflo(x.z), bfhi(x.z), bflo(x.w), bfhi(x.w)};
;                     if (gin) { x0 = x0 * rin[mm] * gv[bj][0]; x1 = x1 * rin[mm] * gv[bj][1]; }
;                     const f32x4 y0 = x0 + a0 * scale, y1 = x1 + a1 * scale;
;                     ss += ((y0[0] * y0[0] + y0[1] * y0[1]) + (y0[2] * y0[2] + y0[3] * y0[3])) + ((y1[0] * y1[0] + y1[1] * y1[1]) + (y1[2] * y1[2] + y1[3] * y1[3]));
;                     if (part2) { const f32x4 z0 = y0 * gv[bj][0], z1 = y1 * gv[bj][1];
;                         ss2 += ((z0[0] * z0[0] + z0[1] * z0[1]) + (z0[2] * z0[2] + z0[3] * z0[3])) + ((z1[0] * z1[0] + z1[1] * z1[1]) + (z1[2] * z1[2] + z1[3] * z1[3])); }
;                     w.x = pg8::cvt_pk_bf16(y0[0], y0[1]); w.y = pg8::cvt_pk_bf16(y0[2], y0[3]); w.z = pg8::cvt_pk_bf16(y1[0], y1[1]); w.w = pg8::cvt_pk_bf16(y1[2], y1[3]);
;                     *(u32x4*)(X + (size_t)(row0 + ai * 128 + (mb + mm) * 16) * D + col0 + bj * 128) = w;
.Lrz_norin_1:
	s_waitcnt vmcnt(8)
	v_lshlrev_b32_e32 v178, 16, v154
	v_and_b32_e32 v179, 0xffff0000, v154
	v_lshlrev_b32_e32 v180, 16, v155
	v_and_b32_e32 v181, 0xffff0000, v155
	v_lshlrev_b32_e32 v182, 16, v156
	v_and_b32_e32 v183, 0xffff0000, v156
	v_lshlrev_b32_e32 v184, 16, v157
	v_and_b32_e32 v185, 0xffff0000, v157
	v_lshlrev_b32_e32 v210, 16, v158
	v_and_b32_e32 v211, 0xffff0000, v158
	v_lshlrev_b32_e32 v212, 16, v159
	v_and_b32_e32 v213, 0xffff0000, v159
	v_lshlrev_b32_e32 v226, 16, v160
	v_and_b32_e32 v227, 0xffff0000, v160
	v_lshlrev_b32_e32 v228, 16, v161
	v_and_b32_e32 v229, 0xffff0000, v161
	v_add_u32_e32 v234, 0x48000, v232
	global_load_dwordx4 v[154:157], v234, s[54:55]
	global_load_dwordx4 v[158:161], v234, s[54:55] offset:256
	s_and_b64 vcc, exec, s[80:81]
	s_cbranch_vccz .Lrz_nolazy_1
	s_waitcnt lgkmcnt(0)
	v_mul_f32_e32 v178, v235, v178
	v_mul_f32_e32 v179, v235, v179
	v_mul_f32_e32 v180, v235, v180
	v_mul_f32_e32 v181, v235, v181
	v_mul_f32_e32 v182, v235, v182
	v_mul_f32_e32 v183, v235, v183
	v_mul_f32_e32 v184, v235, v184
	v_mul_f32_e32 v185, v235, v185
	v_pk_mul_f32 v[178:179], v[178:179], v[40:41]
	v_pk_mul_f32 v[180:181], v[180:181], v[42:43]
	v_pk_mul_f32 v[182:183], v[182:183], v[44:45]
	v_pk_mul_f32 v[184:185], v[184:185], v[46:47]
	v_mul_f32_e32 v210, v235, v210
	v_mul_f32_e32 v211, v235, v211
	v_mul_f32_e32 v212, v235, v212
	v_mul_f32_e32 v213, v235, v213
	v_mul_f32_e32 v226, v235, v226
	v_mul_f32_e32 v227, v235, v227
	v_mul_f32_e32 v228, v235, v228
	v_mul_f32_e32 v229, v235, v229
	v_pk_mul_f32 v[210:211], v[210:211], v[52:53]
	v_pk_mul_f32 v[212:213], v[212:213], v[54:55]
	v_pk_mul_f32 v[226:227], v[226:227], v[60:61]
	v_pk_mul_f32 v[228:229], v[228:229], v[62:63]
.Lrz_nolazy_1:
	v_pk_fma_f32 v[126:127], v[172:173], v[126:127], v[178:179]
	v_pk_fma_f32 v[128:129], v[172:173], v[128:129], v[180:181]
	v_pk_fma_f32 v[122:123], v[172:173], v[122:123], v[182:183]
	v_pk_fma_f32 v[124:125], v[172:173], v[124:125], v[184:185]
	v_pk_fma_f32 v[118:119], v[172:173], v[118:119], v[210:211]
	v_pk_fma_f32 v[120:121], v[172:173], v[120:121], v[212:213]
	v_pk_fma_f32 v[114:115], v[172:173], v[114:115], v[226:227]
	v_pk_fma_f32 v[116:117], v[172:173], v[116:117], v[228:229]
	v_add_u32_e32 v234, 0x8000, v232
	v_cvt_pk_bf16_f32 v178, v126, v127
	v_cvt_pk_bf16_f32 v179, v128, v129
	v_cvt_pk_bf16_f32 v180, v122, v123
	v_cvt_pk_bf16_f32 v181, v124, v125
	global_store_dwordx4 v234, v[178:181], s[54:55]
	v_cvt_pk_bf16_f32 v182, v118, v119
	v_cvt_pk_bf16_f32 v183, v120, v121
	v_cvt_pk_bf16_f32 v184, v114, v115
	v_cvt_pk_bf16_f32 v185, v116, v117
	global_store_dwordx4 v234, v[182:185], s[54:55] offset:256
	v_mul_f32_e32 v210, v126, v126
	v_mul_f32_e32 v211, v127, v127
	v_fmac_f32_e32 v210, v128, v128
	v_fmac_f32_e32 v211, v129, v129
	v_fmac_f32_e32 v210, v122, v122
	v_fmac_f32_e32 v211, v123, v123
	v_fmac_f32_e32 v210, v124, v124
	v_fmac_f32_e32 v211, v125, v125
	v_fmac_f32_e32 v210, v118, v118
	v_fmac_f32_e32 v211, v119, v119
	v_fmac_f32_e32 v210, v120, v120
	v_fmac_f32_e32 v211, v121, v121
	v_fmac_f32_e32 v210, v114, v114
	v_fmac_f32_e32 v211, v115, v115
	v_fmac_f32_e32 v210, v116, v116
	v_fmac_f32_e32 v211, v117, v117
	s_and_b64 vcc, exec, s[74:75]
	s_cbranch_vccz .Lrz_nop2_1
	v_pk_mul_f32 v[212:213], v[126:127], v[40:41]
	v_mul_f32_e32 v226, v212, v212
	v_mul_f32_e32 v227, v213, v213
	v_pk_mul_f32 v[212:213], v[128:129], v[42:43]
	v_fmac_f32_e32 v226, v212, v212
	v_fmac_f32_e32 v227, v213, v213
	v_pk_mul_f32 v[212:213], v[122:123], v[44:45]
	v_fmac_f32_e32 v226, v212, v212
	v_fmac_f32_e32 v227, v213, v213
	v_pk_mul_f32 v[212:213], v[124:125], v[46:47]
	v_fmac_f32_e32 v226, v212, v212
	v_fmac_f32_e32 v227, v213, v213
	v_pk_mul_f32 v[212:213], v[118:119], v[52:53]
	v_fmac_f32_e32 v226, v212, v212
	v_fmac_f32_e32 v227, v213, v213
	v_pk_mul_f32 v[212:213], v[120:121], v[54:55]
	v_fmac_f32_e32 v226, v212, v212
	v_fmac_f32_e32 v227, v213, v213
	v_pk_mul_f32 v[212:213], v[114:115], v[60:61]
	v_fmac_f32_e32 v226, v212, v212
	v_fmac_f32_e32 v227, v213, v213
	v_pk_mul_f32 v[212:213], v[116:117], v[62:63]
	v_fmac_f32_e32 v226, v212, v212
	v_fmac_f32_e32 v227, v213, v213
	v_add_f32_e32 v118, v226, v227
.Lrz_nop2_1:
	v_add_f32_e32 v126, v210, v211
	s_and_b64 vcc, exec, s[80:81]
	s_cbranch_vccz .Lrz_norin_2
	ds_read_b32 v235, v217 offset:128
.Lrz_norin_2:
	s_waitcnt vmcnt(10)
	v_lshlrev_b32_e32 v178, 16, v194
	v_and_b32_e32 v179, 0xffff0000, v194
	v_lshlrev_b32_e32 v180, 16, v195
	v_and_b32_e32 v181, 0xffff0000, v195
	v_lshlrev_b32_e32 v182, 16, v196
	v_and_b32_e32 v183, 0xffff0000, v196
	v_lshlrev_b32_e32 v184, 16, v197
	v_and_b32_e32 v185, 0xffff0000, v197
	v_lshlrev_b32_e32 v210, 16, v198
	v_and_b32_e32 v211, 0xffff0000, v198
	v_lshlrev_b32_e32 v212, 16, v199
	v_and_b32_e32 v213, 0xffff0000, v199
	v_lshlrev_b32_e32 v226, 16, v200
	v_and_b32_e32 v227, 0xffff0000, v200
	v_lshlrev_b32_e32 v228, 16, v201
	v_and_b32_e32 v229, 0xffff0000, v201
	v_add_u32_e32 v234, 0x50000, v232
	global_load_dwordx4 v[194:197], v234, s[54:55]
	global_load_dwordx4 v[198:201], v234, s[54:55] offset:256
	s_and_b64 vcc, exec, s[80:81]
	s_cbranch_vccz .Lrz_nolazy_2
	s_waitcnt lgkmcnt(0)
	v_mul_f32_e32 v178, v235, v178
	v_mul_f32_e32 v179, v235, v179
	v_mul_f32_e32 v180, v235, v180
	v_mul_f32_e32 v181, v235, v181
	v_mul_f32_e32 v182, v235, v182
	v_mul_f32_e32 v183, v235, v183
	v_mul_f32_e32 v184, v235, v184
	v_mul_f32_e32 v185, v235, v185
	v_pk_mul_f32 v[178:179], v[178:179], v[40:41]
	v_pk_mul_f32 v[180:181], v[180:181], v[42:43]
	v_pk_mul_f32 v[182:183], v[182:183], v[44:45]
	v_pk_mul_f32 v[184:185], v[184:185], v[46:47]
	v_mul_f32_e32 v210, v235, v210
	v_mul_f32_e32 v211, v235, v211
	v_mul_f32_e32 v212, v235, v212
	v_mul_f32_e32 v213, v235, v213
	v_mul_f32_e32 v226, v235, v226
	v_mul_f32_e32 v227, v235, v227
	v_mul_f32_e32 v228, v235, v228
	v_mul_f32_e32 v229, v235, v229
	v_pk_mul_f32 v[210:211], v[210:211], v[52:53]
	v_pk_mul_f32 v[212:213], v[212:213], v[54:55]
	v_pk_mul_f32 v[226:227], v[226:227], v[60:61]
	v_pk_mul_f32 v[228:229], v[228:229], v[62:63]
; __device__ __forceinline__ unsigned cvt_pk_bf16(float lo, float hi) { unsigned r; asm volatile("v_cvt_pk_bf16_f32 %0, %1, %2" : "=v"(r) : "v"(lo), "v"(hi)); return r; }
;     __device__ __forceinline__ void operator()(const f32x4 (&acc)[2][2][4][2], const pg8::Unit& u, int wr, int wc, int fr, int fq) const {
;     ...
;         for (int am = 0; am < 4; ++am) {
;             const int ai = am >> 1, mb = (am & 1) * 2;
;             u32x4 xr[2][2]; float rin[2];
; #pragma unroll
;             for (int mm = 0; mm < 2; ++mm) {
;                 rin[mm] = gin ? tabin[u.idx * 256 + wr * 64 + fr + ai * 128 + (mb + mm) * 16] : 1.0f;
; #pragma unroll
;                 for (int bj = 0; bj < 2; ++bj) xr[mm][bj] = *(const u32x4*)(X + (size_t)(row0 + ai * 128 + (mb + mm) * 16) * D + col0 + bj * 128);
;             }
; #pragma unroll
;             for (int mm = 0; mm < 2; ++mm) {
;                 float ss = 0.f, ss2 = 0.f;
; #pragma unroll
;                 for (int bj = 0; bj < 2; ++bj) {
;                     const f32x4 a0 = acc[ai][bj][mb + mm][0], a1 = acc[ai][bj][mb + mm][1]; const u32x4 x = xr[mm][bj]; u32x4 w;
;                     f32x4 x0 = {bflo(x.x), bfhi(x.x), bflo(x.y), bfhi(x.y)}, x1 = {bflo(x.z), bfhi(x.z), bflo(x.w), bfhi(x.w)};
;                     if (gin) { x0 = x0 * rin[mm] * gv[bj][0]; x1 = x1 * rin[mm] * gv[bj][1]; }
;                     const f32x4 y0 = x0 + a0 * scale, y1 = x1 + a1 * scale;
;                     ss += ((y0[0] * y0[0] + y0[1] * y0[1]) + (y0[2] * y0[2] + y0[3] * y0[3])) + ((y1[0] * y1[0] + y1[1] * y1[1]) + (y1[2] * y1[2] + y1[3] * y1[3]));
;                     if (part2) { const f32x4 z0 = y0 * gv[bj][0], z1 = y1 * gv[bj][1];
;                         ss2 += ((z0[0] * z0[0] + z0[1] * z0[1]) + (z0[2] * z0[2] + z0[3] * z0[3])) + ((z1[0] * z1[0] + z1[1] * z1[1]) + (z1[2] * z1[2] + z1[3] * z1[3])); }
;                     w.x = pg8::cvt_pk_bf16(y0[0], y0[1]); w.y = pg8::cvt_pk_bf16(y0[2], y0[3]); w.z = pg8::cvt_pk_bf16(y1[0], y1[1]); w.w = pg8::cvt_pk_bf16(y1[2], y1[3]);
;                     *(u32x4*)(X + (size_t)(row0 + ai * 128 + (mb + mm) * 16) * D + col0 + bj * 128) = w;
.Lrz_nolazy_2:
	v_pk_fma_f32 v[110:111], v[172:173], v[110:111], v[178:179]
	v_pk_fma_f32 v[112:113], v[172:173], v[112:113], v[180:181]
	v_pk_fma_f32 v[106:107], v[172:173], v[106:107], v[182:183]
	v_pk_fma_f32 v[108:109], v[172:173], v[108:109], v[184:185]
	v_pk_fma_f32 v[102:103], v[172:173], v[102:103], v[210:211]
	v_pk_fma_f32 v[104:105], v[172:173], v[104:105], v[212:213]
	v_pk_fma_f32 v[98:99], v[172:173], v[98:99], v[226:227]
	v_pk_fma_f32 v[100:101], v[172:173], v[100:101], v[228:229]
	v_add_u32_e32 v234, 0x10000, v232
	v_cvt_pk_bf16_f32 v178, v110, v111
	v_cvt_pk_bf16_f32 v179, v112, v113
	v_cvt_pk_bf16_f32 v180, v106, v107
	v_cvt_pk_bf16_f32 v181, v108, v109
	global_store_dwordx4 v234, v[178:181], s[54:55]
	v_cvt_pk_bf16_f32 v182, v102, v103
	v_cvt_pk_bf16_f32 v183, v104, v105
	v_cvt_pk_bf16_f32 v184, v98, v99
	v_cvt_pk_bf16_f32 v185, v100, v101
	global_store_dwordx4 v234, v[182:185], s[54:55] offset:256
	v_mul_f32_e32 v210, v110, v110
	v_mul_f32_e32 v211, v111, v111
	v_fmac_f32_e32 v210, v112, v112
	v_fmac_f32_e32 v211, v113, v113
	v_fmac_f32_e32 v210, v106, v106
	v_fmac_f32_e32 v211, v107, v107
	v_fmac_f32_e32 v210, v108, v108
	v_fmac_f32_e32 v211, v109, v109
	v_fmac_f32_e32 v210, v102, v102
	v_fmac_f32_e32 v211, v103, v103
	v_fmac_f32_e32 v210, v104, v104
	v_fmac_f32_e32 v211, v105, v105
	v_fmac_f32_e32 v210, v98, v98
	v_fmac_f32_e32 v211, v99, v99
	v_fmac_f32_e32 v210, v100, v100
	v_fmac_f32_e32 v211, v101, v101
	s_and_b64 vcc, exec, s[74:75]
	s_cbranch_vccz .Lrz_nop2_2
	v_pk_mul_f32 v[212:213], v[110:111], v[40:41]
	v_mul_f32_e32 v226, v212, v212
	v_mul_f32_e32 v227, v213, v213
	v_pk_mul_f32 v[212:213], v[112:113], v[42:43]
	v_fmac_f32_e32 v226, v212, v212
	v_fmac_f32_e32 v227, v213, v213
	v_pk_mul_f32 v[212:213], v[106:107], v[44:45]
	v_fmac_f32_e32 v226, v212, v212
	v_fmac_f32_e32 v227, v213, v213
	v_pk_mul_f32 v[212:213], v[108:109], v[46:47]
	v_fmac_f32_e32 v226, v212, v212
	v_fmac_f32_e32 v227, v213, v213
	v_pk_mul_f32 v[212:213], v[102:103], v[52:53]
	v_fmac_f32_e32 v226, v212, v212
	v_fmac_f32_e32 v227, v213, v213
	v_pk_mul_f32 v[212:213], v[104:105], v[54:55]
	v_fmac_f32_e32 v226, v212, v212
	v_fmac_f32_e32 v227, v213, v213
	v_pk_mul_f32 v[212:213], v[98:99], v[60:61]
	v_fmac_f32_e32 v226, v212, v212
	v_fmac_f32_e32 v227, v213, v213
	v_pk_mul_f32 v[212:213], v[100:101], v[62:63]
	v_fmac_f32_e32 v226, v212, v212
	v_fmac_f32_e32 v227, v213, v213
	v_add_f32_e32 v102, v226, v227
.Lrz_nop2_2:
	v_add_f32_e32 v110, v210, v211
	s_and_b64 vcc, exec, s[80:81]
	s_cbranch_vccz .Lrz_norin_3
	ds_read_b32 v235, v217 offset:192
.Lrz_norin_3:
	s_waitcnt vmcnt(12)
	v_lshlrev_b32_e32 v178, 16, v202
	v_and_b32_e32 v179, 0xffff0000, v202
	v_lshlrev_b32_e32 v180, 16, v203
	v_and_b32_e32 v181, 0xffff0000, v203
	v_lshlrev_b32_e32 v182, 16, v204
	v_and_b32_e32 v183, 0xffff0000, v204
	v_lshlrev_b32_e32 v184, 16, v205
	v_and_b32_e32 v185, 0xffff0000, v205
	v_lshlrev_b32_e32 v210, 16, v206
	v_and_b32_e32 v211, 0xffff0000, v206
	v_lshlrev_b32_e32 v212, 16, v207
	v_and_b32_e32 v213, 0xffff0000, v207
	v_lshlrev_b32_e32 v226, 16, v208
	v_and_b32_e32 v227, 0xffff0000, v208
	v_lshlrev_b32_e32 v228, 16, v209
	v_and_b32_e32 v229, 0xffff0000, v209
	v_add_u32_e32 v234, 0x58000, v232
	global_load_dwordx4 v[202:205], v234, s[54:55]
	global_load_dwordx4 v[206:209], v234, s[54:55] offset:256
	s_and_b64 vcc, exec, s[80:81]
	s_cbranch_vccz .Lrz_nolazy_3
	s_waitcnt lgkmcnt(0)
	v_mul_f32_e32 v178, v235, v178
	v_mul_f32_e32 v179, v235, v179
	v_mul_f32_e32 v180, v235, v180
	v_mul_f32_e32 v181, v235, v181
	v_mul_f32_e32 v182, v235, v182
	v_mul_f32_e32 v183, v235, v183
	v_mul_f32_e32 v184, v235, v184
	v_mul_f32_e32 v185, v235, v185
	v_pk_mul_f32 v[178:179], v[178:179], v[40:41]
	v_pk_mul_f32 v[180:181], v[180:181], v[42:43]
	v_pk_mul_f32 v[182:183], v[182:183], v[44:45]
	v_pk_mul_f32 v[184:185], v[184:185], v[46:47]
	v_mul_f32_e32 v210, v235, v210
	v_mul_f32_e32 v211, v235, v211
	v_mul_f32_e32 v212, v235, v212
	v_mul_f32_e32 v213, v235, v213
	v_mul_f32_e32 v226, v235, v226
	v_mul_f32_e32 v227, v235, v227
	v_mul_f32_e32 v228, v235, v228
	v_mul_f32_e32 v229, v235, v229
	v_pk_mul_f32 v[210:211], v[210:211], v[52:53]
	v_pk_mul_f32 v[212:213], v[212:213], v[54:55]
	v_pk_mul_f32 v[226:227], v[226:227], v[60:61]
	v_pk_mul_f32 v[228:229], v[228:229], v[62:63]
.Lrz_nolazy_3:
	v_pk_fma_f32 v[94:95], v[172:173], v[94:95], v[178:179]
	v_pk_fma_f32 v[96:97], v[172:173], v[96:97], v[180:181]
	v_pk_fma_f32 v[90:91], v[172:173], v[90:91], v[182:183]
	v_pk_fma_f32 v[92:93], v[172:173], v[92:93], v[184:185]
	v_pk_fma_f32 v[86:87], v[172:173], v[86:87], v[210:211]
	v_pk_fma_f32 v[88:89], v[172:173], v[88:89], v[212:213]
	v_pk_fma_f32 v[82:83], v[172:173], v[82:83], v[226:227]
	v_pk_fma_f32 v[84:85], v[172:173], v[84:85], v[228:229]
	v_add_u32_e32 v234, 0x18000, v232
	v_cvt_pk_bf16_f32 v178, v94, v95
	v_cvt_pk_bf16_f32 v179, v96, v97
	v_cvt_pk_bf16_f32 v180, v90, v91
	v_cvt_pk_bf16_f32 v181, v92, v93
	global_store_dwordx4 v234, v[178:181], s[54:55]
	v_cvt_pk_bf16_f32 v182, v86, v87
	v_cvt_pk_bf16_f32 v183, v88, v89
	v_cvt_pk_bf16_f32 v184, v82, v83
	v_cvt_pk_bf16_f32 v185, v84, v85
	global_store_dwordx4 v234, v[182:185], s[54:55] offset:256
	v_mul_f32_e32 v210, v94, v94
	v_mul_f32_e32 v211, v95, v95
	v_fmac_f32_e32 v210, v96, v96
	v_fmac_f32_e32 v211, v97, v97
	v_fmac_f32_e32 v210, v90, v90
	v_fmac_f32_e32 v211, v91, v91
	v_fmac_f32_e32 v210, v92, v92
	v_fmac_f32_e32 v211, v93, v93
	v_fmac_f32_e32 v210, v86, v86
	v_fmac_f32_e32 v211, v87, v87
	v_fmac_f32_e32 v210, v88, v88
	v_fmac_f32_e32 v211, v89, v89
	v_fmac_f32_e32 v210, v82, v82
	v_fmac_f32_e32 v211, v83, v83
	v_fmac_f32_e32 v210, v84, v84
	v_fmac_f32_e32 v211, v85, v85
	s_and_b64 vcc, exec, s[74:75]
	s_cbranch_vccz .Lrz_nop2_3
	v_pk_mul_f32 v[212:213], v[94:95], v[40:41]
	v_mul_f32_e32 v226, v212, v212
	v_mul_f32_e32 v227, v213, v213
	v_pk_mul_f32 v[212:213], v[96:97], v[42:43]
	v_fmac_f32_e32 v226, v212, v212
	v_fmac_f32_e32 v227, v213, v213
	v_pk_mul_f32 v[212:213], v[90:91], v[44:45]
	v_fmac_f32_e32 v226, v212, v212
	v_fmac_f32_e32 v227, v213, v213
	v_pk_mul_f32 v[212:213], v[92:93], v[46:47]
	v_fmac_f32_e32 v226, v212, v212
	v_fmac_f32_e32 v227, v213, v213
	v_pk_mul_f32 v[212:213], v[86:87], v[52:53]
	v_fmac_f32_e32 v226, v212, v212
	v_fmac_f32_e32 v227, v213, v213
	v_pk_mul_f32 v[212:213], v[88:89], v[54:55]
	v_fmac_f32_e32 v226, v212, v212
	v_fmac_f32_e32 v227, v213, v213
	v_pk_mul_f32 v[212:213], v[82:83], v[60:61]
	v_fmac_f32_e32 v226, v212, v212
	v_fmac_f32_e32 v227, v213, v213
	v_pk_mul_f32 v[212:213], v[84:85], v[62:63]
	v_fmac_f32_e32 v226, v212, v212
	v_fmac_f32_e32 v227, v213, v213
	v_add_f32_e32 v86, v226, v227
; __device__ __forceinline__ unsigned cvt_pk_bf16(float lo, float hi) { unsigned r; asm volatile("v_cvt_pk_bf16_f32 %0, %1, %2" : "=v"(r) : "v"(lo), "v"(hi)); return r; }
;     __device__ __forceinline__ void operator()(const f32x4 (&acc)[2][2][4][2], const pg8::Unit& u, int wr, int wc, int fr, int fq) const {
;     ...
;         for (int am = 0; am < 4; ++am) {
;             const int ai = am >> 1, mb = (am & 1) * 2;
;             u32x4 xr[2][2]; float rin[2];
; #pragma unroll
;             for (int mm = 0; mm < 2; ++mm) {
;                 rin[mm] = gin ? tabin[u.idx * 256 + wr * 64 + fr + ai * 128 + (mb + mm) * 16] : 1.0f;
; #pragma unroll
;                 for (int bj = 0; bj < 2; ++bj) xr[mm][bj] = *(const u32x4*)(X + (size_t)(row0 + ai * 128 + (mb + mm) * 16) * D + col0 + bj * 128);
;             }
; #pragma unroll
;             for (int mm = 0; mm < 2; ++mm) {
;                 float ss = 0.f, ss2 = 0.f;
; #pragma unroll
;                 for (int bj = 0; bj < 2; ++bj) {
;                     const f32x4 a0 = acc[ai][bj][mb + mm][0], a1 = acc[ai][bj][mb + mm][1]; const u32x4 x = xr[mm][bj]; u32x4 w;
;                     f32x4 x0 = {bflo(x.x), bfhi(x.x), bflo(x.y), bfhi(x.y)}, x1 = {bflo(x.z), bfhi(x.z), bflo(x.w), bfhi(x.w)};
;                     if (gin) { x0 = x0 * rin[mm] * gv[bj][0]; x1 = x1 * rin[mm] * gv[bj][1]; }
;                     const f32x4 y0 = x0 + a0 * scale, y1 = x1 + a1 * scale;
;                     ss += ((y0[0] * y0[0] + y0[1] * y0[1]) + (y0[2] * y0[2] + y0[3] * y0[3])) + ((y1[0] * y1[0] + y1[1] * y1[1]) + (y1[2] * y1[2] + y1[3] * y1[3]));
;                     if (part2) { const f32x4 z0 = y0 * gv[bj][0], z1 = y1 * gv[bj][1];
;                         ss2 += ((z0[0] * z0[0] + z0[1] * z0[1]) + (z0[2] * z0[2] + z0[3] * z0[3])) + ((z1[0] * z1[0] + z1[1] * z1[1]) + (z1[2] * z1[2] + z1[3] * z1[3])); }
;                     w.x = pg8::cvt_pk_bf16(y0[0], y0[1]); w.y = pg8::cvt_pk_bf16(y0[2], y0[3]); w.z = pg8::cvt_pk_bf16(y1[0], y1[1]); w.w = pg8::cvt_pk_bf16(y1[2], y1[3]);
;                     *(u32x4*)(X + (size_t)(row0 + ai * 128 + (mb + mm) * 16) * D + col0 + bj * 128) = w;
.Lrz_nop2_3:
	v_add_f32_e32 v94, v210, v211
	s_and_b64 vcc, exec, s[80:81]
	s_cbranch_vccz .Lrz_norin_4
	ds_read_b32 v235, v217 offset:512
.Lrz_norin_4:
	s_waitcnt vmcnt(14)
	v_lshlrev_b32_e32 v178, 16, v146
	v_and_b32_e32 v179, 0xffff0000, v146
	v_lshlrev_b32_e32 v180, 16, v147
	v_and_b32_e32 v181, 0xffff0000, v147
	v_lshlrev_b32_e32 v182, 16, v148
	v_and_b32_e32 v183, 0xffff0000, v148
	v_lshlrev_b32_e32 v184, 16, v149
	v_and_b32_e32 v185, 0xffff0000, v149
	v_lshlrev_b32_e32 v210, 16, v150
	v_and_b32_e32 v211, 0xffff0000, v150
	v_lshlrev_b32_e32 v212, 16, v151
	v_and_b32_e32 v213, 0xffff0000, v151
	v_lshlrev_b32_e32 v226, 16, v152
	v_and_b32_e32 v227, 0xffff0000, v152
	v_lshlrev_b32_e32 v228, 16, v153
	v_and_b32_e32 v229, 0xffff0000, v153
	s_and_b64 vcc, exec, s[80:81]
	s_cbranch_vccz .Lrz_nolazy_4
	s_waitcnt lgkmcnt(0)
	v_mul_f32_e32 v178, v235, v178
	v_mul_f32_e32 v179, v235, v179
	v_mul_f32_e32 v180, v235, v180
	v_mul_f32_e32 v181, v235, v181
	v_mul_f32_e32 v182, v235, v182
	v_mul_f32_e32 v183, v235, v183
	v_mul_f32_e32 v184, v235, v184
	v_mul_f32_e32 v185, v235, v185
	v_pk_mul_f32 v[178:179], v[178:179], v[40:41]
	v_pk_mul_f32 v[180:181], v[180:181], v[42:43]
	v_pk_mul_f32 v[182:183], v[182:183], v[44:45]
	v_pk_mul_f32 v[184:185], v[184:185], v[46:47]
	v_mul_f32_e32 v210, v235, v210
	v_mul_f32_e32 v211, v235, v211
	v_mul_f32_e32 v212, v235, v212
	v_mul_f32_e32 v213, v235, v213
	v_mul_f32_e32 v226, v235, v226
	v_mul_f32_e32 v227, v235, v227
	v_mul_f32_e32 v228, v235, v228
	v_mul_f32_e32 v229, v235, v229
	v_pk_mul_f32 v[210:211], v[210:211], v[52:53]
	v_pk_mul_f32 v[212:213], v[212:213], v[54:55]
	v_pk_mul_f32 v[226:227], v[226:227], v[60:61]
	v_pk_mul_f32 v[228:229], v[228:229], v[62:63]
.Lrz_nolazy_4:
	v_pk_fma_f32 v[76:77], v[172:173], v[76:77], v[178:179]
	v_pk_fma_f32 v[78:79], v[172:173], v[78:79], v[180:181]
	v_pk_fma_f32 v[72:73], v[172:173], v[72:73], v[182:183]
	v_pk_fma_f32 v[74:75], v[172:173], v[74:75], v[184:185]
	v_pk_fma_f32 v[68:69], v[172:173], v[68:69], v[210:211]
	v_pk_fma_f32 v[70:71], v[172:173], v[70:71], v[212:213]
	v_pk_fma_f32 v[64:65], v[172:173], v[64:65], v[226:227]
	v_pk_fma_f32 v[66:67], v[172:173], v[66:67], v[228:229]
	v_add_u32_e32 v234, 0x40000, v232
	v_cvt_pk_bf16_f32 v178, v76, v77
	v_cvt_pk_bf16_f32 v179, v78, v79
	v_cvt_pk_bf16_f32 v180, v72, v73
	v_cvt_pk_bf16_f32 v181, v74, v75
	global_store_dwordx4 v234, v[178:181], s[54:55]
	v_cvt_pk_bf16_f32 v182, v68, v69
	v_cvt_pk_bf16_f32 v183, v70, v71
	v_cvt_pk_bf16_f32 v184, v64, v65
	v_cvt_pk_bf16_f32 v185, v66, v67
	global_store_dwordx4 v234, v[182:185], s[54:55] offset:256
	v_mul_f32_e32 v210, v76, v76
	v_mul_f32_e32 v211, v77, v77
	v_fmac_f32_e32 v210, v78, v78
	v_fmac_f32_e32 v211, v79, v79
	v_fmac_f32_e32 v210, v72, v72
	v_fmac_f32_e32 v211, v73, v73
	v_fmac_f32_e32 v210, v74, v74
	v_fmac_f32_e32 v211, v75, v75
	v_fmac_f32_e32 v210, v68, v68
	v_fmac_f32_e32 v211, v69, v69
	v_fmac_f32_e32 v210, v70, v70
	v_fmac_f32_e32 v211, v71, v71
	v_fmac_f32_e32 v210, v64, v64
	v_fmac_f32_e32 v211, v65, v65
	v_fmac_f32_e32 v210, v66, v66
	v_fmac_f32_e32 v211, v67, v67
	s_and_b64 vcc, exec, s[74:75]
	s_cbranch_vccz .Lrz_nop2_4
	v_pk_mul_f32 v[212:213], v[76:77], v[40:41]
	v_mul_f32_e32 v226, v212, v212
	v_mul_f32_e32 v227, v213, v213
	v_pk_mul_f32 v[212:213], v[78:79], v[42:43]
	v_fmac_f32_e32 v226, v212, v212
	v_fmac_f32_e32 v227, v213, v213
	v_pk_mul_f32 v[212:213], v[72:73], v[44:45]
	v_fmac_f32_e32 v226, v212, v212
	v_fmac_f32_e32 v227, v213, v213
	v_pk_mul_f32 v[212:213], v[74:75], v[46:47]
	v_fmac_f32_e32 v226, v212, v212
	v_fmac_f32_e32 v227, v213, v213
	v_pk_mul_f32 v[212:213], v[68:69], v[52:53]
	v_fmac_f32_e32 v226, v212, v212
	v_fmac_f32_e32 v227, v213, v213
	v_pk_mul_f32 v[212:213], v[70:71], v[54:55]
	v_fmac_f32_e32 v226, v212, v212
	v_fmac_f32_e32 v227, v213, v213
	v_pk_mul_f32 v[212:213], v[64:65], v[60:61]
	v_fmac_f32_e32 v226, v212, v212
	v_fmac_f32_e32 v227, v213, v213
	v_pk_mul_f32 v[212:213], v[66:67], v[62:63]
	v_fmac_f32_e32 v226, v212, v212
	v_fmac_f32_e32 v227, v213, v213
	v_add_f32_e32 v68, v226, v227
.Lrz_nop2_4:
	v_add_f32_e32 v76, v210, v211
	s_and_b64 vcc, exec, s[80:81]
	s_cbranch_vccz .Lrz_norin_5
	ds_read_b32 v235, v217 offset:576
.Lrz_norin_5:
	s_waitcnt vmcnt(12)
	v_lshlrev_b32_e32 v178, 16, v154
	v_and_b32_e32 v179, 0xffff0000, v154
	v_lshlrev_b32_e32 v180, 16, v155
	v_and_b32_e32 v181, 0xffff0000, v155
	v_lshlrev_b32_e32 v182, 16, v156
	v_and_b32_e32 v183, 0xffff0000, v156
	v_lshlrev_b32_e32 v184, 16, v157
	v_and_b32_e32 v185, 0xffff0000, v157
	v_lshlrev_b32_e32 v210, 16, v158
	v_and_b32_e32 v211, 0xffff0000, v158
	v_lshlrev_b32_e32 v212, 16, v159
	v_and_b32_e32 v213, 0xffff0000, v159
	v_lshlrev_b32_e32 v226, 16, v160
	v_and_b32_e32 v227, 0xffff0000, v160
	v_lshlrev_b32_e32 v228, 16, v161
	v_and_b32_e32 v229, 0xffff0000, v161
	s_and_b64 vcc, exec, s[80:81]
	s_cbranch_vccz .Lrz_nolazy_5
	s_waitcnt lgkmcnt(0)
	v_mul_f32_e32 v178, v235, v178
	v_mul_f32_e32 v179, v235, v179
	v_mul_f32_e32 v180, v235, v180
	v_mul_f32_e32 v181, v235, v181
	v_mul_f32_e32 v182, v235, v182
	v_mul_f32_e32 v183, v235, v183
	v_mul_f32_e32 v184, v235, v184
	v_mul_f32_e32 v185, v235, v185
	v_pk_mul_f32 v[178:179], v[178:179], v[40:41]
	v_pk_mul_f32 v[180:181], v[180:181], v[42:43]
	v_pk_mul_f32 v[182:183], v[182:183], v[44:45]
	v_pk_mul_f32 v[184:185], v[184:185], v[46:47]
	v_mul_f32_e32 v210, v235, v210
	v_mul_f32_e32 v211, v235, v211
	v_mul_f32_e32 v212, v235, v212
	v_mul_f32_e32 v213, v235, v213
	v_mul_f32_e32 v226, v235, v226
	v_mul_f32_e32 v227, v235, v227
	v_mul_f32_e32 v228, v235, v228
	v_mul_f32_e32 v229, v235, v229
	v_pk_mul_f32 v[210:211], v[210:211], v[52:53]
	v_pk_mul_f32 v[212:213], v[212:213], v[54:55]
	v_pk_mul_f32 v[226:227], v[226:227], v[60:61]
	v_pk_mul_f32 v[228:229], v[228:229], v[62:63]
; __device__ __forceinline__ unsigned cvt_pk_bf16(float lo, float hi) { unsigned r; asm volatile("v_cvt_pk_bf16_f32 %0, %1, %2" : "=v"(r) : "v"(lo), "v"(hi)); return r; }
;     __device__ __forceinline__ void operator()(const f32x4 (&acc)[2][2][4][2], const pg8::Unit& u, int wr, int wc, int fr, int fq) const {
;     ...
;         for (int am = 0; am < 4; ++am) {
;             const int ai = am >> 1, mb = (am & 1) * 2;
;             u32x4 xr[2][2]; float rin[2];
; #pragma unroll
;             for (int mm = 0; mm < 2; ++mm) {
;                 rin[mm] = gin ? tabin[u.idx * 256 + wr * 64 + fr + ai * 128 + (mb + mm) * 16] : 1.0f;
; #pragma unroll
;                 for (int bj = 0; bj < 2; ++bj) xr[mm][bj] = *(const u32x4*)(X + (size_t)(row0 + ai * 128 + (mb + mm) * 16) * D + col0 + bj * 128);
;             }
; #pragma unroll
;             for (int mm = 0; mm < 2; ++mm) {
;                 float ss = 0.f, ss2 = 0.f;
; #pragma unroll
;                 for (int bj = 0; bj < 2; ++bj) {
;                     const f32x4 a0 = acc[ai][bj][mb + mm][0], a1 = acc[ai][bj][mb + mm][1]; const u32x4 x = xr[mm][bj]; u32x4 w;
;                     f32x4 x0 = {bflo(x.x), bfhi(x.x), bflo(x.y), bfhi(x.y)}, x1 = {bflo(x.z), bfhi(x.z), bflo(x.w), bfhi(x.w)};
;                     if (gin) { x0 = x0 * rin[mm] * gv[bj][0]; x1 = x1 * rin[mm] * gv[bj][1]; }
;                     const f32x4 y0 = x0 + a0 * scale, y1 = x1 + a1 * scale;
;                     ss += ((y0[0] * y0[0] + y0[1] * y0[1]) + (y0[2] * y0[2] + y0[3] * y0[3])) + ((y1[0] * y1[0] + y1[1] * y1[1]) + (y1[2] * y1[2] + y1[3] * y1[3]));
;                     if (part2) { const f32x4 z0 = y0 * gv[bj][0], z1 = y1 * gv[bj][1];
;                         ss2 += ((z0[0] * z0[0] + z0[1] * z0[1]) + (z0[2] * z0[2] + z0[3] * z0[3])) + ((z1[0] * z1[0] + z1[1] * z1[1]) + (z1[2] * z1[2] + z1[3] * z1[3])); }
;                     w.x = pg8::cvt_pk_bf16(y0[0], y0[1]); w.y = pg8::cvt_pk_bf16(y0[2], y0[3]); w.z = pg8::cvt_pk_bf16(y1[0], y1[1]); w.w = pg8::cvt_pk_bf16(y1[2], y1[3]);
;                     *(u32x4*)(X + (size_t)(row0 + ai * 128 + (mb + mm) * 16) * D + col0 + bj * 128) = w;
.Lrz_nolazy_5:
	v_pk_fma_f32 v[56:57], v[172:173], v[56:57], v[178:179]
	v_pk_fma_f32 v[58:59], v[172:173], v[58:59], v[180:181]
	v_pk_fma_f32 v[48:49], v[172:173], v[48:49], v[182:183]
	v_pk_fma_f32 v[50:51], v[172:173], v[50:51], v[184:185]
	v_pk_fma_f32 v[36:37], v[172:173], v[36:37], v[210:211]
	v_pk_fma_f32 v[38:39], v[172:173], v[38:39], v[212:213]
	v_pk_fma_f32 v[32:33], v[172:173], v[32:33], v[226:227]
	v_pk_fma_f32 v[34:35], v[172:173], v[34:35], v[228:229]
	v_add_u32_e32 v234, 0x48000, v232
	v_cvt_pk_bf16_f32 v178, v56, v57
	v_cvt_pk_bf16_f32 v179, v58, v59
	v_cvt_pk_bf16_f32 v180, v48, v49
	v_cvt_pk_bf16_f32 v181, v50, v51
	global_store_dwordx4 v234, v[178:181], s[54:55]
	v_cvt_pk_bf16_f32 v182, v36, v37
	v_cvt_pk_bf16_f32 v183, v38, v39
	v_cvt_pk_bf16_f32 v184, v32, v33
	v_cvt_pk_bf16_f32 v185, v34, v35
	global_store_dwordx4 v234, v[182:185], s[54:55] offset:256
	v_mul_f32_e32 v210, v56, v56
	v_mul_f32_e32 v211, v57, v57
	v_fmac_f32_e32 v210, v58, v58
	v_fmac_f32_e32 v211, v59, v59
	v_fmac_f32_e32 v210, v48, v48
	v_fmac_f32_e32 v211, v49, v49
	v_fmac_f32_e32 v210, v50, v50
	v_fmac_f32_e32 v211, v51, v51
	v_fmac_f32_e32 v210, v36, v36
	v_fmac_f32_e32 v211, v37, v37
	v_fmac_f32_e32 v210, v38, v38
	v_fmac_f32_e32 v211, v39, v39
	v_fmac_f32_e32 v210, v32, v32
	v_fmac_f32_e32 v211, v33, v33
	v_fmac_f32_e32 v210, v34, v34
	v_fmac_f32_e32 v211, v35, v35
	s_and_b64 vcc, exec, s[74:75]
	s_cbranch_vccz .Lrz_nop2_5
	v_pk_mul_f32 v[212:213], v[56:57], v[40:41]
	v_mul_f32_e32 v226, v212, v212
	v_mul_f32_e32 v227, v213, v213
	v_pk_mul_f32 v[212:213], v[58:59], v[42:43]
	v_fmac_f32_e32 v226, v212, v212
	v_fmac_f32_e32 v227, v213, v213
	v_pk_mul_f32 v[212:213], v[48:49], v[44:45]
	v_fmac_f32_e32 v226, v212, v212
	v_fmac_f32_e32 v227, v213, v213
	v_pk_mul_f32 v[212:213], v[50:51], v[46:47]
	v_fmac_f32_e32 v226, v212, v212
	v_fmac_f32_e32 v227, v213, v213
	v_pk_mul_f32 v[212:213], v[36:37], v[52:53]
	v_fmac_f32_e32 v226, v212, v212
	v_fmac_f32_e32 v227, v213, v213
	v_pk_mul_f32 v[212:213], v[38:39], v[54:55]
	v_fmac_f32_e32 v226, v212, v212
	v_fmac_f32_e32 v227, v213, v213
	v_pk_mul_f32 v[212:213], v[32:33], v[60:61]
	v_fmac_f32_e32 v226, v212, v212
	v_fmac_f32_e32 v227, v213, v213
	v_pk_mul_f32 v[212:213], v[34:35], v[62:63]
	v_fmac_f32_e32 v226, v212, v212
	v_fmac_f32_e32 v227, v213, v213
	v_add_f32_e32 v36, v226, v227
.Lrz_nop2_5:
	v_add_f32_e32 v56, v210, v211
	s_and_b64 vcc, exec, s[80:81]
	s_cbranch_vccz .Lrz_norin_6
	ds_read_b32 v235, v217 offset:640
.Lrz_norin_6:
	s_waitcnt vmcnt(10)
	v_lshlrev_b32_e32 v178, 16, v194
	v_and_b32_e32 v179, 0xffff0000, v194
	v_lshlrev_b32_e32 v180, 16, v195
	v_and_b32_e32 v181, 0xffff0000, v195
	v_lshlrev_b32_e32 v182, 16, v196
	v_and_b32_e32 v183, 0xffff0000, v196
	v_lshlrev_b32_e32 v184, 16, v197
	v_and_b32_e32 v185, 0xffff0000, v197
	v_lshlrev_b32_e32 v210, 16, v198
	v_and_b32_e32 v211, 0xffff0000, v198
	v_lshlrev_b32_e32 v212, 16, v199
	v_and_b32_e32 v213, 0xffff0000, v199
	v_lshlrev_b32_e32 v226, 16, v200
	v_and_b32_e32 v227, 0xffff0000, v200
	v_lshlrev_b32_e32 v228, 16, v201
	v_and_b32_e32 v229, 0xffff0000, v201
	s_and_b64 vcc, exec, s[80:81]
	s_cbranch_vccz .Lrz_nolazy_6
	s_waitcnt lgkmcnt(0)
	v_mul_f32_e32 v178, v235, v178
	v_mul_f32_e32 v179, v235, v179
	v_mul_f32_e32 v180, v235, v180
	v_mul_f32_e32 v181, v235, v181
	v_mul_f32_e32 v182, v235, v182
	v_mul_f32_e32 v183, v235, v183
	v_mul_f32_e32 v184, v235, v184
	v_mul_f32_e32 v185, v235, v185
	v_pk_mul_f32 v[178:179], v[178:179], v[40:41]
	v_pk_mul_f32 v[180:181], v[180:181], v[42:43]
	v_pk_mul_f32 v[182:183], v[182:183], v[44:45]
	v_pk_mul_f32 v[184:185], v[184:185], v[46:47]
	v_mul_f32_e32 v210, v235, v210
	v_mul_f32_e32 v211, v235, v211
	v_mul_f32_e32 v212, v235, v212
	v_mul_f32_e32 v213, v235, v213
	v_mul_f32_e32 v226, v235, v226
	v_mul_f32_e32 v227, v235, v227
	v_mul_f32_e32 v228, v235, v228
	v_mul_f32_e32 v229, v235, v229
	v_pk_mul_f32 v[210:211], v[210:211], v[52:53]
	v_pk_mul_f32 v[212:213], v[212:213], v[54:55]
	v_pk_mul_f32 v[226:227], v[226:227], v[60:61]
	v_pk_mul_f32 v[228:229], v[228:229], v[62:63]
.Lrz_nolazy_6:
	v_pk_fma_f32 v[28:29], v[172:173], v[28:29], v[178:179]
	v_pk_fma_f32 v[30:31], v[172:173], v[30:31], v[180:181]
	v_pk_fma_f32 v[24:25], v[172:173], v[24:25], v[182:183]
	v_pk_fma_f32 v[26:27], v[172:173], v[26:27], v[184:185]
	v_pk_fma_f32 v[20:21], v[172:173], v[20:21], v[210:211]
	v_pk_fma_f32 v[22:23], v[172:173], v[22:23], v[212:213]
	v_pk_fma_f32 v[16:17], v[172:173], v[16:17], v[226:227]
	v_pk_fma_f32 v[18:19], v[172:173], v[18:19], v[228:229]
	v_add_u32_e32 v234, 0x50000, v232
	v_cvt_pk_bf16_f32 v178, v28, v29
	v_cvt_pk_bf16_f32 v179, v30, v31
	v_cvt_pk_bf16_f32 v180, v24, v25
	v_cvt_pk_bf16_f32 v181, v26, v27
	global_store_dwordx4 v234, v[178:181], s[54:55]
	v_cvt_pk_bf16_f32 v182, v20, v21
	v_cvt_pk_bf16_f32 v183, v22, v23
	v_cvt_pk_bf16_f32 v184, v16, v17
	v_cvt_pk_bf16_f32 v185, v18, v19
	global_store_dwordx4 v234, v[182:185], s[54:55] offset:256
	v_mul_f32_e32 v210, v28, v28
	v_mul_f32_e32 v211, v29, v29
	v_fmac_f32_e32 v210, v30, v30
	v_fmac_f32_e32 v211, v31, v31
	v_fmac_f32_e32 v210, v24, v24
	v_fmac_f32_e32 v211, v25, v25
	v_fmac_f32_e32 v210, v26, v26
	v_fmac_f32_e32 v211, v27, v27
	v_fmac_f32_e32 v210, v20, v20
	v_fmac_f32_e32 v211, v21, v21
	v_fmac_f32_e32 v210, v22, v22
	v_fmac_f32_e32 v211, v23, v23
	v_fmac_f32_e32 v210, v16, v16
	v_fmac_f32_e32 v211, v17, v17
	v_fmac_f32_e32 v210, v18, v18
	v_fmac_f32_e32 v211, v19, v19
	s_and_b64 vcc, exec, s[74:75]
	s_cbranch_vccz .Lrz_nop2_6
	v_pk_mul_f32 v[212:213], v[28:29], v[40:41]
	v_mul_f32_e32 v226, v212, v212
	v_mul_f32_e32 v227, v213, v213
	v_pk_mul_f32 v[212:213], v[30:31], v[42:43]
	v_fmac_f32_e32 v226, v212, v212
	v_fmac_f32_e32 v227, v213, v213
	v_pk_mul_f32 v[212:213], v[24:25], v[44:45]
	v_fmac_f32_e32 v226, v212, v212
	v_fmac_f32_e32 v227, v213, v213
	v_pk_mul_f32 v[212:213], v[26:27], v[46:47]
	v_fmac_f32_e32 v226, v212, v212
	v_fmac_f32_e32 v227, v213, v213
	v_pk_mul_f32 v[212:213], v[20:21], v[52:53]
	v_fmac_f32_e32 v226, v212, v212
	v_fmac_f32_e32 v227, v213, v213
	v_pk_mul_f32 v[212:213], v[22:23], v[54:55]
	v_fmac_f32_e32 v226, v212, v212
	v_fmac_f32_e32 v227, v213, v213
	v_pk_mul_f32 v[212:213], v[16:17], v[60:61]
	v_fmac_f32_e32 v226, v212, v212
	v_fmac_f32_e32 v227, v213, v213
	v_pk_mul_f32 v[212:213], v[18:19], v[62:63]
	v_fmac_f32_e32 v226, v212, v212
	v_fmac_f32_e32 v227, v213, v213
	v_add_f32_e32 v20, v226, v227
; __device__ __forceinline__ unsigned cvt_pk_bf16(float lo, float hi) { unsigned r; asm volatile("v_cvt_pk_bf16_f32 %0, %1, %2" : "=v"(r) : "v"(lo), "v"(hi)); return r; }
;     __device__ __forceinline__ void operator()(const f32x4 (&acc)[2][2][4][2], const pg8::Unit& u, int wr, int wc, int fr, int fq) const {
;     ...
;         for (int am = 0; am < 4; ++am) {
;             const int ai = am >> 1, mb = (am & 1) * 2;
;             u32x4 xr[2][2]; float rin[2];
; #pragma unroll
;             for (int mm = 0; mm < 2; ++mm) {
;                 rin[mm] = gin ? tabin[u.idx * 256 + wr * 64 + fr + ai * 128 + (mb + mm) * 16] : 1.0f;
; #pragma unroll
;                 for (int bj = 0; bj < 2; ++bj) xr[mm][bj] = *(const u32x4*)(X + (size_t)(row0 + ai * 128 + (mb + mm) * 16) * D + col0 + bj * 128);
;             }
; #pragma unroll
;             for (int mm = 0; mm < 2; ++mm) {
;                 float ss = 0.f, ss2 = 0.f;
; #pragma unroll
;                 for (int bj = 0; bj < 2; ++bj) {
;                     const f32x4 a0 = acc[ai][bj][mb + mm][0], a1 = acc[ai][bj][mb + mm][1]; const u32x4 x = xr[mm][bj]; u32x4 w;
;                     f32x4 x0 = {bflo(x.x), bfhi(x.x), bflo(x.y), bfhi(x.y)}, x1 = {bflo(x.z), bfhi(x.z), bflo(x.w), bfhi(x.w)};
;                     if (gin) { x0 = x0 * rin[mm] * gv[bj][0]; x1 = x1 * rin[mm] * gv[bj][1]; }
;                     const f32x4 y0 = x0 + a0 * scale, y1 = x1 + a1 * scale;
;                     ss += ((y0[0] * y0[0] + y0[1] * y0[1]) + (y0[2] * y0[2] + y0[3] * y0[3])) + ((y1[0] * y1[0] + y1[1] * y1[1]) + (y1[2] * y1[2] + y1[3] * y1[3]));
;                     if (part2) { const f32x4 z0 = y0 * gv[bj][0], z1 = y1 * gv[bj][1];
;                         ss2 += ((z0[0] * z0[0] + z0[1] * z0[1]) + (z0[2] * z0[2] + z0[3] * z0[3])) + ((z1[0] * z1[0] + z1[1] * z1[1]) + (z1[2] * z1[2] + z1[3] * z1[3])); }
;                     w.x = pg8::cvt_pk_bf16(y0[0], y0[1]); w.y = pg8::cvt_pk_bf16(y0[2], y0[3]); w.z = pg8::cvt_pk_bf16(y1[0], y1[1]); w.w = pg8::cvt_pk_bf16(y1[2], y1[3]);
;                     *(u32x4*)(X + (size_t)(row0 + ai * 128 + (mb + mm) * 16) * D + col0 + bj * 128) = w;
.Lrz_nop2_6:
	v_add_f32_e32 v28, v210, v211
	s_and_b64 vcc, exec, s[80:81]
	s_cbranch_vccz .Lrz_norin_7
	ds_read_b32 v235, v217 offset:704
.Lrz_norin_7:
	s_waitcnt vmcnt(8)
	v_lshlrev_b32_e32 v178, 16, v202
	v_and_b32_e32 v179, 0xffff0000, v202
	v_lshlrev_b32_e32 v180, 16, v203
	v_and_b32_e32 v181, 0xffff0000, v203
	v_lshlrev_b32_e32 v182, 16, v204
	v_and_b32_e32 v183, 0xffff0000, v204
	v_lshlrev_b32_e32 v184, 16, v205
	v_and_b32_e32 v185, 0xffff0000, v205
	v_lshlrev_b32_e32 v210, 16, v206
	v_and_b32_e32 v211, 0xffff0000, v206
	v_lshlrev_b32_e32 v212, 16, v207
	v_and_b32_e32 v213, 0xffff0000, v207
	v_lshlrev_b32_e32 v226, 16, v208
	v_and_b32_e32 v227, 0xffff0000, v208
	v_lshlrev_b32_e32 v228, 16, v209
	v_and_b32_e32 v229, 0xffff0000, v209
	s_and_b64 vcc, exec, s[80:81]
	s_cbranch_vccz .Lrz_nolazy_7
	s_waitcnt lgkmcnt(0)
	v_mul_f32_e32 v178, v235, v178
	v_mul_f32_e32 v179, v235, v179
	v_mul_f32_e32 v180, v235, v180
	v_mul_f32_e32 v181, v235, v181
	v_mul_f32_e32 v182, v235, v182
	v_mul_f32_e32 v183, v235, v183
	v_mul_f32_e32 v184, v235, v184
	v_mul_f32_e32 v185, v235, v185
	v_pk_mul_f32 v[178:179], v[178:179], v[40:41]
	v_pk_mul_f32 v[180:181], v[180:181], v[42:43]
	v_pk_mul_f32 v[182:183], v[182:183], v[44:45]
	v_pk_mul_f32 v[184:185], v[184:185], v[46:47]
	v_mul_f32_e32 v210, v235, v210
	v_mul_f32_e32 v211, v235, v211
	v_mul_f32_e32 v212, v235, v212
	v_mul_f32_e32 v213, v235, v213
	v_mul_f32_e32 v226, v235, v226
	v_mul_f32_e32 v227, v235, v227
	v_mul_f32_e32 v228, v235, v228
	v_mul_f32_e32 v229, v235, v229
	v_pk_mul_f32 v[210:211], v[210:211], v[52:53]
	v_pk_mul_f32 v[212:213], v[212:213], v[54:55]
	v_pk_mul_f32 v[226:227], v[226:227], v[60:61]
	v_pk_mul_f32 v[228:229], v[228:229], v[62:63]
.Lrz_nolazy_7:
	v_pk_fma_f32 v[12:13], v[172:173], v[12:13], v[178:179]
	v_pk_fma_f32 v[14:15], v[172:173], v[14:15], v[180:181]
	v_pk_fma_f32 v[8:9], v[172:173], v[8:9], v[182:183]
	v_pk_fma_f32 v[10:11], v[172:173], v[10:11], v[184:185]
	v_pk_fma_f32 v[4:5], v[172:173], v[4:5], v[210:211]
	v_pk_fma_f32 v[6:7], v[172:173], v[6:7], v[212:213]
	v_pk_fma_f32 v[0:1], v[172:173], v[0:1], v[226:227]
	v_pk_fma_f32 v[2:3], v[172:173], v[2:3], v[228:229]
	v_add_u32_e32 v234, 0x58000, v232
	v_cvt_pk_bf16_f32 v178, v12, v13
	v_cvt_pk_bf16_f32 v179, v14, v15
	v_cvt_pk_bf16_f32 v180, v8, v9
	v_cvt_pk_bf16_f32 v181, v10, v11
	global_store_dwordx4 v234, v[178:181], s[54:55]
	v_cvt_pk_bf16_f32 v182, v4, v5
	v_cvt_pk_bf16_f32 v183, v6, v7
	v_cvt_pk_bf16_f32 v184, v0, v1
	v_cvt_pk_bf16_f32 v185, v2, v3
	global_store_dwordx4 v234, v[182:185], s[54:55] offset:256
	v_mul_f32_e32 v210, v12, v12
	v_mul_f32_e32 v211, v13, v13
	v_fmac_f32_e32 v210, v14, v14
	v_fmac_f32_e32 v211, v15, v15
	v_fmac_f32_e32 v210, v8, v8
	v_fmac_f32_e32 v211, v9, v9
	v_fmac_f32_e32 v210, v10, v10
	v_fmac_f32_e32 v211, v11, v11
	v_fmac_f32_e32 v210, v4, v4
	v_fmac_f32_e32 v211, v5, v5
	v_fmac_f32_e32 v210, v6, v6
	v_fmac_f32_e32 v211, v7, v7
	v_fmac_f32_e32 v210, v0, v0
	v_fmac_f32_e32 v211, v1, v1
	v_fmac_f32_e32 v210, v2, v2
	v_fmac_f32_e32 v211, v3, v3
	s_and_b64 vcc, exec, s[74:75]
	s_cbranch_vccz .Lrz_nop2_7
	v_pk_mul_f32 v[212:213], v[12:13], v[40:41]
	v_mul_f32_e32 v226, v212, v212
	v_mul_f32_e32 v227, v213, v213
	v_pk_mul_f32 v[212:213], v[14:15], v[42:43]
	v_fmac_f32_e32 v226, v212, v212
	v_fmac_f32_e32 v227, v213, v213
	v_pk_mul_f32 v[212:213], v[8:9], v[44:45]
	v_fmac_f32_e32 v226, v212, v212
	v_fmac_f32_e32 v227, v213, v213
	v_pk_mul_f32 v[212:213], v[10:11], v[46:47]
	v_fmac_f32_e32 v226, v212, v212
	v_fmac_f32_e32 v227, v213, v213
	v_pk_mul_f32 v[212:213], v[4:5], v[52:53]
	v_fmac_f32_e32 v226, v212, v212
	v_fmac_f32_e32 v227, v213, v213
	v_pk_mul_f32 v[212:213], v[6:7], v[54:55]
	v_fmac_f32_e32 v226, v212, v212
	v_fmac_f32_e32 v227, v213, v213
	v_pk_mul_f32 v[212:213], v[0:1], v[60:61]
	v_fmac_f32_e32 v226, v212, v212
	v_fmac_f32_e32 v227, v213, v213
	v_pk_mul_f32 v[212:213], v[2:3], v[62:63]
	v_fmac_f32_e32 v226, v212, v212
	v_fmac_f32_e32 v227, v213, v213
	v_add_f32_e32 v4, v226, v227
; #define PG8_BAR __builtin_amdgcn_s_barrier()
; template <class Epi, class Sched, bool ALIGN_EPI = false, bool SP2 = false>
; __device__ __forceinline__ void gemm_phase(PG8_LAS unsigned char* lds, const Gemm g, const Sched& S, const Epi& E, int tid_in) {
;     ...
;         if (!has_next) break;
; #pragma unroll
;         for (int a = 0; a < 2; ++a)
; #pragma unroll
;             for (int b = 0; b < 2; ++b)
; #pragma unroll
;                 for (int m = 0; m < 4; ++m)
; #pragma unroll
;                     for (int n = 0; n < 2; ++n) acc[a][b][m][n] = (f32x4){0.f, 0.f, 0.f, 0.f};
;         cur = nxt; cA = nA; cB = nB; ++ui;
;         if constexpr (ALIGN_EPI) { if (wr == 1) PG8_BAR; }
;     __device__ __forceinline__ void operator()(const f32x4 (&acc)[2][2][4][2], const pg8::Unit& u, int wr, int wc, int fr, int fq) const {
;     ...
;                 if (part) { ss += __shfl_xor(ss, 16); ss += __shfl_xor(ss, 32); if (fq == 0) part[(size_t)(row0 + ai * 128 + (mb + mm) * 16) * 16 + u.pn * 4 + wc] = ss; }
;                 if (part2) { ss2 += __shfl_xor(ss2, 16); ss2 += __shfl_xor(ss2, 32); if (fq == 0) part2[(size_t)(row0 + ai * 128 + (mb + mm) * 16) * 16 + u.pn * 4 + wc] = ss2; }
;             }
;             asm volatile("" ::: "memory");
.Lrz_nop2_7:
	v_add_f32_e32 v12, v210, v211
	s_and_b64 vcc, exec, s[86:87]
	s_cbranch_vccz .Lrz_nopart
	ds_bpermute_b32 v146, v248, v142
	ds_bpermute_b32 v147, v248, v126
	ds_bpermute_b32 v148, v248, v110
	ds_bpermute_b32 v149, v248, v94
	ds_bpermute_b32 v150, v248, v76
	ds_bpermute_b32 v151, v248, v56
	ds_bpermute_b32 v152, v248, v28
	ds_bpermute_b32 v153, v248, v12
	s_waitcnt lgkmcnt(0)
	v_add_f32_e32 v142, v142, v146
	v_add_f32_e32 v126, v126, v147
	v_add_f32_e32 v110, v110, v148
	v_add_f32_e32 v94, v94, v149
	v_add_f32_e32 v76, v76, v150
	v_add_f32_e32 v56, v56, v151
	v_add_f32_e32 v28, v28, v152
	v_add_f32_e32 v12, v12, v153
	ds_bpermute_b32 v146, v249, v142
	ds_bpermute_b32 v147, v249, v126
	ds_bpermute_b32 v148, v249, v110
	ds_bpermute_b32 v149, v249, v94
	ds_bpermute_b32 v150, v249, v76
	ds_bpermute_b32 v151, v249, v56
	ds_bpermute_b32 v152, v249, v28
	ds_bpermute_b32 v153, v249, v12
	s_waitcnt lgkmcnt(0)
	s_and_saveexec_b64 s[92:93], s[36:37]
	v_add_f32_e32 v146, v142, v146
	v_add_u32_e32 v154, 0x0, v233
	v_add_f32_e32 v147, v126, v147
	v_add_u32_e32 v155, 0x400, v233
	v_add_f32_e32 v148, v110, v148
	v_add_u32_e32 v156, 0x800, v233
	v_add_f32_e32 v149, v94, v149
	v_add_u32_e32 v157, 0xc00, v233
	v_add_f32_e32 v150, v76, v150
	v_add_u32_e32 v158, 0x2000, v233
	v_add_f32_e32 v151, v56, v151
	v_add_u32_e32 v159, 0x2400, v233
	v_add_f32_e32 v152, v28, v152
	v_add_u32_e32 v160, 0x2800, v233
	v_add_f32_e32 v153, v12, v153
	v_add_u32_e32 v161, 0x2c00, v233
	global_store_dword v154, v146, s[76:77]
	global_store_dword v155, v147, s[76:77]
	global_store_dword v156, v148, s[76:77]
	global_store_dword v157, v149, s[76:77]
	global_store_dword v158, v150, s[76:77]
	global_store_dword v159, v151, s[76:77]
	global_store_dword v160, v152, s[76:77]
	global_store_dword v161, v153, s[76:77]
	s_or_b64 exec, exec, s[92:93]
.Lrz_nopart:
	s_and_b64 vcc, exec, s[74:75]
	s_cbranch_vccz .Lrz_nopart2
	v_readlane_b32 s40, v253, 61
	v_readlane_b32 s41, v253, 62
	ds_bpermute_b32 v146, v248, v134
	ds_bpermute_b32 v147, v248, v118
	ds_bpermute_b32 v148, v248, v102
	ds_bpermute_b32 v149, v248, v86
	ds_bpermute_b32 v150, v248, v68
	ds_bpermute_b32 v151, v248, v36
	ds_bpermute_b32 v152, v248, v20
	ds_bpermute_b32 v153, v248, v4
	s_waitcnt lgkmcnt(0)
	v_add_f32_e32 v134, v134, v146
	v_add_f32_e32 v118, v118, v147
	v_add_f32_e32 v102, v102, v148
	v_add_f32_e32 v86, v86, v149
	v_add_f32_e32 v68, v68, v150
	v_add_f32_e32 v36, v36, v151
	v_add_f32_e32 v20, v20, v152
	v_add_f32_e32 v4, v4, v153
	ds_bpermute_b32 v146, v249, v134
	ds_bpermute_b32 v147, v249, v118
	ds_bpermute_b32 v148, v249, v102
	ds_bpermute_b32 v149, v249, v86
	ds_bpermute_b32 v150, v249, v68
	ds_bpermute_b32 v151, v249, v36
	ds_bpermute_b32 v152, v249, v20
	ds_bpermute_b32 v153, v249, v4
	s_waitcnt lgkmcnt(0)
	s_and_saveexec_b64 s[92:93], s[36:37]
	v_add_f32_e32 v146, v134, v146
	v_add_u32_e32 v154, 0x0, v233
	v_add_f32_e32 v147, v118, v147
	v_add_u32_e32 v155, 0x400, v233
	v_add_f32_e32 v148, v102, v148
	v_add_u32_e32 v156, 0x800, v233
	v_add_f32_e32 v149, v86, v149
	v_add_u32_e32 v157, 0xc00, v233
	v_add_f32_e32 v150, v68, v150
	v_add_u32_e32 v158, 0x2000, v233
	v_add_f32_e32 v151, v36, v151
	v_add_u32_e32 v159, 0x2400, v233
	v_add_f32_e32 v152, v20, v152
	v_add_u32_e32 v160, 0x2800, v233
	v_add_f32_e32 v153, v4, v153
	v_add_u32_e32 v161, 0x2c00, v233
	global_store_dword v154, v146, s[40:41]
	global_store_dword v155, v147, s[40:41]
	global_store_dword v156, v148, s[40:41]
	global_store_dword v157, v149, s[40:41]
	global_store_dword v158, v150, s[40:41]
	global_store_dword v159, v151, s[40:41]
	global_store_dword v160, v152, s[40:41]
	global_store_dword v161, v153, s[40:41]
	s_or_b64 exec, exec, s[92:93]
.Lrz_nopart2:
.LBB0_663:
	s_and_b64 vcc, exec, s[38:39]
	s_mov_b64 s[38:39], -1
	s_cbranch_vccnz .LBB0_500
	v_readlane_b32 s26, v254, 17
	v_readlane_b32 s27, v254, 18
	s_andn2_b64 vcc, exec, s[26:27]
	s_cbranch_vccnz .LBB0_499
	s_barrier
	s_branch .LBB0_499
